# P10 K-loop LDS-DMA pieces use SGPR base + 32-bit lane offset addressing (16 fewer 64-bit VALU adds per iteration)
# baseline (speedup 1.0000x reference)
; #define PG8_STAGE(bufoff, gbase, voff) do { _Pragma("unroll") for (int _i = 0; _i < 2; ++_i) \
;         __builtin_amdgcn_global_load_lds((const unsigned*)((const char*)(gbase) + (voff)[_i]), (PG8_LAS unsigned*)(lds + (bufoff) + ldsw + _i * 8192), 16, 0, 0); } while (0)
; #define PG8_LDA(dst, b, h) do { _Pragma("unroll") for (int m = 0; m < 4; ++m) _Pragma("unroll") for (int k = 0; k < 2; ++k) dst[m][k] = *(const PG8_LAS bf16x8*)(lds + PG8_SA(b, h) + aoff + m * 2048 + k * 1024); } while (0)
; #define PG8_LDB(dst, b, h) do { _Pragma("unroll") for (int n = 0; n < 2; ++n) _Pragma("unroll") for (int k = 0; k < 2; ++k) dst[n][k] = *(const PG8_LAS bf16x8*)(lds + PG8_SB(b, h) + boff + n * 2048 + k * 1024); } while (0)
; #define PG8_MMA(ai, bj, At, Bt) do { __builtin_amdgcn_s_setprio(1); _Pragma("unroll") for (int m = 0; m < 4; ++m) _Pragma("unroll") for (int n = 0; n < 2; ++n) _Pragma("unroll") for (int k = 0; k < 2; ++k) \
;         acc[ai][bj][m][n] = __builtin_amdgcn_mfma_f32_16x16x32_bf16(Bt[n][k], At[m][k], acc[ai][bj][m][n], 0, 0, 0); __builtin_amdgcn_s_setprio(0); } while (0)
; #define PG8_WAIT_V(n) asm volatile("s_waitcnt vmcnt(" #n ")" ::: "memory")
; #define PG8_WAIT_L(n) asm volatile("s_waitcnt lgkmcnt(" #n ")" ::: "memory")
; #define PG8_BAR __builtin_amdgcn_s_barrier()
; #define PG8_SCHED __builtin_amdgcn_sched_barrier(0)
; template <class Epi, class Sched, bool ALIGN_EPI = false, bool SP2 = false>
; __device__ __forceinline__ void gemm_phase(PG8_LAS unsigned char* lds, const Gemm g, const Sched& S, const Epi& E) {
;     ...
;             PG8_LDB(B0, 0, 0); PG8_LDB(B1, 0, 1); PG8_SCHED; PG8_LDA(At, 0, 0); PG8_STAGE(PG8_SA(1, 1), a1 + hstep, voffA);
;             PG8_WAIT_V(8); PG8_WAIT_L(0); PG8_BAR; PG8_MMA(0, 0, At, B0); PG8_MMA(0, 1, At, B1); PG8_BAR; PG8_SCHED;
;             PG8_LDA(At, 0, 1); PG8_STAGE(PG8_SB(0, 0), b2, voffB); PG8_STAGE(PG8_SB(0, 1), b2 + hstep, voffB); PG8_STAGE(PG8_SA(0, 0), a2, voffA);
;             PG8_WAIT_V(8); PG8_WAIT_L(0); PG8_BAR; PG8_MMA(1, 0, At, B0); PG8_MMA(1, 1, At, B1); PG8_BAR; PG8_SCHED;
.LBB0_1823:
	ds_read_b128 v[144:147], v155
	ds_read_b128 v[148:151], v155 offset:1024
	ds_read_b128 v[160:163], v155 offset:2048
	ds_read_b128 v[164:167], v155 offset:3072
	ds_read_b128 v[168:171], v156
	ds_read_b128 v[172:175], v156 offset:1024
	ds_read_b128 v[176:179], v156 offset:2048
	ds_read_b128 v[180:183], v156 offset:3072
	s_add_u32 s34, s26, 0xfffc0080
	s_addc_u32 s35, s27, -1
	s_cmp_eq_u32 s58, 12
	s_cselect_b32 s37, s12, s35
	s_cselect_b32 s36, s13, s34
	s_cselect_b32 s35, s17, s57
	s_cselect_b32 s34, s19, s56
	s_add_i32 m0, s25, 0xc000
	ds_read_b128 v[184:187], v157
	ds_read_b128 v[188:191], v157 offset:1024
	ds_read_b128 v[192:195], v157 offset:2048
	ds_read_b128 v[198:201], v157 offset:3072
	ds_read_b128 v[202:205], v157 offset:4096
	ds_read_b128 v[206:209], v157 offset:5120
	ds_read_b128 v[210:213], v157 offset:6144
	ds_read_b128 v[214:217], v157 offset:7168
	global_load_lds_dwordx4 v138, s[26:27]
	s_add_i32 m0, s25, 0xe000
	s_nop 0
	global_load_lds_dwordx4 v136, s[26:27]
	s_waitcnt vmcnt(8)
	s_waitcnt lgkmcnt(0)
	s_barrier
	s_setprio 1
	s_waitcnt lgkmcnt(0)
	v_mfma_f32_16x16x32_bf16 v[124:127], v[144:147], v[184:187], v[124:127]
	v_mfma_f32_16x16x32_bf16 v[120:123], v[160:163], v[184:187], v[120:123]
	v_mfma_f32_16x16x32_bf16 v[108:111], v[144:147], v[192:195], v[108:111]
	v_mfma_f32_16x16x32_bf16 v[104:107], v[160:163], v[192:195], v[104:107]
	v_mfma_f32_16x16x32_bf16 v[92:95], v[144:147], v[202:205], v[92:95]
	v_mfma_f32_16x16x32_bf16 v[88:91], v[160:163], v[202:205], v[88:91]
	v_mfma_f32_16x16x32_bf16 v[76:79], v[144:147], v[210:213], v[76:79]
	v_mfma_f32_16x16x32_bf16 v[72:75], v[160:163], v[210:213], v[72:75]
	v_mfma_f32_16x16x32_bf16 v[124:127], v[148:151], v[188:191], v[124:127]
	v_mfma_f32_16x16x32_bf16 v[120:123], v[164:167], v[188:191], v[120:123]
	v_mfma_f32_16x16x32_bf16 v[108:111], v[148:151], v[198:201], v[108:111]
	v_mfma_f32_16x16x32_bf16 v[104:107], v[164:167], v[198:201], v[104:107]
	v_mfma_f32_16x16x32_bf16 v[92:95], v[148:151], v[206:209], v[92:95]
	v_mfma_f32_16x16x32_bf16 v[88:91], v[164:167], v[206:209], v[88:91]
	v_mfma_f32_16x16x32_bf16 v[76:79], v[148:151], v[214:217], v[76:79]
	v_mfma_f32_16x16x32_bf16 v[72:75], v[164:167], v[214:217], v[72:75]
	s_setprio 0
	s_setprio 1
	v_mfma_f32_16x16x32_bf16 v[116:119], v[168:171], v[184:187], v[116:119]
	v_mfma_f32_16x16x32_bf16 v[112:115], v[176:179], v[184:187], v[112:115]
	v_mfma_f32_16x16x32_bf16 v[100:103], v[168:171], v[192:195], v[100:103]
	v_mfma_f32_16x16x32_bf16 v[96:99], v[176:179], v[192:195], v[96:99]
	v_mfma_f32_16x16x32_bf16 v[84:87], v[168:171], v[202:205], v[84:87]
	v_mfma_f32_16x16x32_bf16 v[80:83], v[176:179], v[202:205], v[80:83]
	v_mfma_f32_16x16x32_bf16 v[68:71], v[168:171], v[210:213], v[68:71]
	v_mfma_f32_16x16x32_bf16 v[64:67], v[176:179], v[210:213], v[64:67]
	v_mfma_f32_16x16x32_bf16 v[116:119], v[172:175], v[188:191], v[116:119]
	v_mfma_f32_16x16x32_bf16 v[112:115], v[180:183], v[188:191], v[112:115]
	v_mfma_f32_16x16x32_bf16 v[100:103], v[172:175], v[198:201], v[100:103]
	v_mfma_f32_16x16x32_bf16 v[96:99], v[180:183], v[198:201], v[96:99]
	v_mfma_f32_16x16x32_bf16 v[84:87], v[172:175], v[206:209], v[84:87]
	v_mfma_f32_16x16x32_bf16 v[80:83], v[180:183], v[206:209], v[80:83]
	v_mfma_f32_16x16x32_bf16 v[68:71], v[172:175], v[214:217], v[68:71]
	v_mfma_f32_16x16x32_bf16 v[64:67], v[180:183], v[214:217], v[64:67]
	s_setprio 0
	s_barrier
	s_add_i32 s59, s52, s41
	s_mov_b32 m0, s59
	ds_read_b128 v[184:187], v157 offset:16384
	ds_read_b128 v[188:191], v157 offset:17408
	ds_read_b128 v[192:195], v157 offset:18432
	ds_read_b128 v[198:201], v157 offset:19456
	ds_read_b128 v[202:205], v157 offset:20480
	ds_read_b128 v[206:209], v157 offset:21504
	ds_read_b128 v[210:213], v157 offset:22528
	ds_read_b128 v[214:217], v157 offset:23552
	global_load_lds_dwordx4 v130, s[34:35]
	s_add_i32 m0, s59, 0x2000
	s_add_u32 s60, s34, 0x40000
	s_addc_u32 s61, s35, 0
	s_add_i32 s59, s53, s41
	global_load_lds_dwordx4 v134, s[34:35]
	s_add_u32 s98, s34, s10
	s_mov_b32 m0, s59
	s_addc_u32 s99, s35, s11
	global_load_lds_dwordx4 v130, s[60:61]
	s_add_u32 s100, s36, s10
	s_addc_u32 s101, s37, s11
	s_add_i32 m0, s59, 0x2000
	s_nop 0
	global_load_lds_dwordx4 v134, s[60:61]
	s_mov_b32 m0, s25
	s_nop 0
	global_load_lds_dwordx4 v128, s[36:37]
	s_mov_b32 m0, s44
	s_nop 0
	global_load_lds_dwordx4 v132, s[36:37]
	s_waitcnt vmcnt(8)
	s_waitcnt lgkmcnt(0)
	s_barrier
	s_setprio 1
	s_waitcnt lgkmcnt(0)
	v_mfma_f32_16x16x32_bf16 v[60:63], v[144:147], v[184:187], v[60:63]
	v_mfma_f32_16x16x32_bf16 v[56:59], v[160:163], v[184:187], v[56:59]
	v_mfma_f32_16x16x32_bf16 v[44:47], v[144:147], v[192:195], v[44:47]
	v_mfma_f32_16x16x32_bf16 v[40:43], v[160:163], v[192:195], v[40:43]
	v_mfma_f32_16x16x32_bf16 v[28:31], v[144:147], v[202:205], v[28:31]
	v_mfma_f32_16x16x32_bf16 v[24:27], v[160:163], v[202:205], v[24:27]
	v_mfma_f32_16x16x32_bf16 v[12:15], v[144:147], v[210:213], v[12:15]
	v_mfma_f32_16x16x32_bf16 v[8:11], v[160:163], v[210:213], v[8:11]
	v_mfma_f32_16x16x32_bf16 v[60:63], v[148:151], v[188:191], v[60:63]
	v_mfma_f32_16x16x32_bf16 v[56:59], v[164:167], v[188:191], v[56:59]
	v_mfma_f32_16x16x32_bf16 v[44:47], v[148:151], v[198:201], v[44:47]
	v_mfma_f32_16x16x32_bf16 v[40:43], v[164:167], v[198:201], v[40:43]
	v_mfma_f32_16x16x32_bf16 v[28:31], v[148:151], v[206:209], v[28:31]
	v_mfma_f32_16x16x32_bf16 v[24:27], v[164:167], v[206:209], v[24:27]
	v_mfma_f32_16x16x32_bf16 v[12:15], v[148:151], v[214:217], v[12:15]
	v_mfma_f32_16x16x32_bf16 v[8:11], v[164:167], v[214:217], v[8:11]
	s_setprio 0
	s_setprio 1
	v_mfma_f32_16x16x32_bf16 v[52:55], v[168:171], v[184:187], v[52:55]
	v_mfma_f32_16x16x32_bf16 v[48:51], v[176:179], v[184:187], v[48:51]
	v_mfma_f32_16x16x32_bf16 v[36:39], v[168:171], v[192:195], v[36:39]
	v_mfma_f32_16x16x32_bf16 v[32:35], v[176:179], v[192:195], v[32:35]
	v_mfma_f32_16x16x32_bf16 v[20:23], v[168:171], v[202:205], v[20:23]
	v_mfma_f32_16x16x32_bf16 v[16:19], v[176:179], v[202:205], v[16:19]
	v_mfma_f32_16x16x32_bf16 v[4:7], v[168:171], v[210:213], v[4:7]
	v_mfma_f32_16x16x32_bf16 v[0:3], v[176:179], v[210:213], v[0:3]
	v_mfma_f32_16x16x32_bf16 v[52:55], v[172:175], v[188:191], v[52:55]
	v_mfma_f32_16x16x32_bf16 v[48:51], v[180:183], v[188:191], v[48:51]
	v_mfma_f32_16x16x32_bf16 v[36:39], v[172:175], v[198:201], v[36:39]
	v_mfma_f32_16x16x32_bf16 v[32:35], v[180:183], v[198:201], v[32:35]
	v_mfma_f32_16x16x32_bf16 v[20:23], v[172:175], v[206:209], v[20:23]
	v_mfma_f32_16x16x32_bf16 v[16:19], v[180:183], v[206:209], v[16:19]
	v_mfma_f32_16x16x32_bf16 v[4:7], v[172:175], v[214:217], v[4:7]
	v_mfma_f32_16x16x32_bf16 v[0:3], v[180:183], v[214:217], v[0:3]
	s_setprio 0
	s_barrier
; #define PG8_STAGE(bufoff, gbase, voff) do { _Pragma("unroll") for (int _i = 0; _i < 2; ++_i) \
;         __builtin_amdgcn_global_load_lds((const unsigned*)((const char*)(gbase) + (voff)[_i]), (PG8_LAS unsigned*)(lds + (bufoff) + ldsw + _i * 8192), 16, 0, 0); } while (0)
; #define PG8_LDA(dst, b, h) do { _Pragma("unroll") for (int m = 0; m < 4; ++m) _Pragma("unroll") for (int k = 0; k < 2; ++k) dst[m][k] = *(const PG8_LAS bf16x8*)(lds + PG8_SA(b, h) + aoff + m * 2048 + k * 1024); } while (0)
; #define PG8_LDB(dst, b, h) do { _Pragma("unroll") for (int n = 0; n < 2; ++n) _Pragma("unroll") for (int k = 0; k < 2; ++k) dst[n][k] = *(const PG8_LAS bf16x8*)(lds + PG8_SB(b, h) + boff + n * 2048 + k * 1024); } while (0)
; #define PG8_MMA(ai, bj, At, Bt) do { __builtin_amdgcn_s_setprio(1); _Pragma("unroll") for (int m = 0; m < 4; ++m) _Pragma("unroll") for (int n = 0; n < 2; ++n) _Pragma("unroll") for (int k = 0; k < 2; ++k) \
;         acc[ai][bj][m][n] = __builtin_amdgcn_mfma_f32_16x16x32_bf16(Bt[n][k], At[m][k], acc[ai][bj][m][n], 0, 0, 0); __builtin_amdgcn_s_setprio(0); } while (0)
; #define PG8_WAIT_V(n) asm volatile("s_waitcnt vmcnt(" #n ")" ::: "memory")
; #define PG8_WAIT_L(n) asm volatile("s_waitcnt lgkmcnt(" #n ")" ::: "memory")
; #define PG8_BAR __builtin_amdgcn_s_barrier()
; #define PG8_SCHED __builtin_amdgcn_sched_barrier(0)
; template <class Epi, class Sched, bool ALIGN_EPI = false, bool SP2 = false>
; __device__ __forceinline__ void gemm_phase(PG8_LAS unsigned char* lds, const Gemm g, const Sched& S, const Epi& E) {
;     ...
;             PG8_LDB(B0, 1, 0); PG8_LDB(B1, 1, 1); PG8_SCHED; PG8_LDA(At, 1, 0); PG8_STAGE(PG8_SA(0, 1), a2 + hstep, voffA);
;             PG8_WAIT_V(8); PG8_WAIT_L(0); PG8_BAR; PG8_MMA(0, 0, At, B0); PG8_MMA(0, 1, At, B1); PG8_BAR; PG8_SCHED;
;             PG8_LDA(At, 1, 1); PG8_STAGE(PG8_SB(1, 0), b3, voffB); PG8_STAGE(PG8_SB(1, 1), b3 + hstep, voffB); PG8_STAGE(PG8_SA(1, 0), a3, voffA);
;             PG8_WAIT_V(8); PG8_WAIT_L(0); PG8_BAR; PG8_MMA(1, 0, At, B0); PG8_MMA(1, 1, At, B1); PG8_BAR; PG8_SCHED;
	s_add_i32 s59, 0, 0x18000
	v_add_u32_e32 v159, s59, v153
	s_add_i32 s60, 0, 0x1c000
	ds_read_b128 v[144:147], v159
	ds_read_b128 v[148:151], v159 offset:1024
	ds_read_b128 v[160:163], v159 offset:2048
	ds_read_b128 v[164:167], v159 offset:3072
	v_add_u32_e32 v159, s60, v153
	ds_read_b128 v[168:171], v159
	ds_read_b128 v[172:175], v159 offset:1024
	ds_read_b128 v[176:179], v159 offset:2048
	ds_read_b128 v[180:183], v159 offset:3072
	s_add_u32 s36, s36, 0x40000
	s_addc_u32 s37, s37, 0
	s_mov_b32 m0, s45
	ds_read_b128 v[184:187], v157 offset:32768
	ds_read_b128 v[188:191], v157 offset:33792
	ds_read_b128 v[192:195], v157 offset:34816
	ds_read_b128 v[198:201], v157 offset:35840
	ds_read_b128 v[202:205], v157 offset:36864
	ds_read_b128 v[206:209], v157 offset:37888
	ds_read_b128 v[210:213], v157 offset:38912
	ds_read_b128 v[214:217], v157 offset:39936
	global_load_lds_dwordx4 v128, s[36:37]
	s_mov_b32 m0, s46
	s_nop 0
	global_load_lds_dwordx4 v132, s[36:37]
	s_waitcnt vmcnt(8)
	s_waitcnt lgkmcnt(0)
	s_barrier
	s_setprio 1
	s_waitcnt lgkmcnt(0)
	v_mfma_f32_16x16x32_bf16 v[124:127], v[144:147], v[184:187], v[124:127]
	v_mfma_f32_16x16x32_bf16 v[120:123], v[160:163], v[184:187], v[120:123]
	v_mfma_f32_16x16x32_bf16 v[108:111], v[144:147], v[192:195], v[108:111]
	v_mfma_f32_16x16x32_bf16 v[104:107], v[160:163], v[192:195], v[104:107]
	v_mfma_f32_16x16x32_bf16 v[92:95], v[144:147], v[202:205], v[92:95]
	v_mfma_f32_16x16x32_bf16 v[88:91], v[160:163], v[202:205], v[88:91]
	v_mfma_f32_16x16x32_bf16 v[76:79], v[144:147], v[210:213], v[76:79]
	v_mfma_f32_16x16x32_bf16 v[72:75], v[160:163], v[210:213], v[72:75]
	v_mfma_f32_16x16x32_bf16 v[124:127], v[148:151], v[188:191], v[124:127]
	v_mfma_f32_16x16x32_bf16 v[120:123], v[164:167], v[188:191], v[120:123]
	v_mfma_f32_16x16x32_bf16 v[108:111], v[148:151], v[198:201], v[108:111]
	v_mfma_f32_16x16x32_bf16 v[104:107], v[164:167], v[198:201], v[104:107]
	v_mfma_f32_16x16x32_bf16 v[92:95], v[148:151], v[206:209], v[92:95]
	v_mfma_f32_16x16x32_bf16 v[88:91], v[164:167], v[206:209], v[88:91]
	v_mfma_f32_16x16x32_bf16 v[76:79], v[148:151], v[214:217], v[76:79]
	v_mfma_f32_16x16x32_bf16 v[72:75], v[164:167], v[214:217], v[72:75]
	s_setprio 0
	s_setprio 1
	v_mfma_f32_16x16x32_bf16 v[116:119], v[168:171], v[184:187], v[116:119]
	v_mfma_f32_16x16x32_bf16 v[112:115], v[176:179], v[184:187], v[112:115]
	v_mfma_f32_16x16x32_bf16 v[100:103], v[168:171], v[192:195], v[100:103]
	v_mfma_f32_16x16x32_bf16 v[96:99], v[176:179], v[192:195], v[96:99]
	v_mfma_f32_16x16x32_bf16 v[84:87], v[168:171], v[202:205], v[84:87]
	v_mfma_f32_16x16x32_bf16 v[80:83], v[176:179], v[202:205], v[80:83]
	v_mfma_f32_16x16x32_bf16 v[68:71], v[168:171], v[210:213], v[68:71]
	v_mfma_f32_16x16x32_bf16 v[64:67], v[176:179], v[210:213], v[64:67]
	v_mfma_f32_16x16x32_bf16 v[116:119], v[172:175], v[188:191], v[116:119]
	v_mfma_f32_16x16x32_bf16 v[112:115], v[180:183], v[188:191], v[112:115]
	v_mfma_f32_16x16x32_bf16 v[100:103], v[172:175], v[198:201], v[100:103]
	v_mfma_f32_16x16x32_bf16 v[96:99], v[180:183], v[198:201], v[96:99]
	v_mfma_f32_16x16x32_bf16 v[84:87], v[172:175], v[206:209], v[84:87]
	v_mfma_f32_16x16x32_bf16 v[80:83], v[180:183], v[206:209], v[80:83]
	v_mfma_f32_16x16x32_bf16 v[68:71], v[172:175], v[214:217], v[68:71]
	v_mfma_f32_16x16x32_bf16 v[64:67], v[180:183], v[214:217], v[64:67]
	s_setprio 0
	s_barrier
	s_add_i32 s36, s59, s41
	s_mov_b32 m0, s36
	ds_read_b128 v[184:187], v157 offset:49152
	ds_read_b128 v[188:191], v157 offset:50176
	ds_read_b128 v[192:195], v157 offset:51200
	ds_read_b128 v[198:201], v157 offset:52224
	ds_read_b128 v[202:205], v157 offset:53248
	ds_read_b128 v[206:209], v157 offset:54272
	ds_read_b128 v[210:213], v157 offset:55296
	ds_read_b128 v[214:217], v157 offset:56320
	global_load_lds_dwordx4 v130, s[98:99]
	s_add_i32 m0, s36, 0x2000
	s_add_u32 s34, s34, 0x40080
	s_addc_u32 s35, s35, 0
	s_add_i32 s36, s60, s41
	global_load_lds_dwordx4 v134, s[98:99]
	s_mov_b32 m0, s36
	s_nop 0
	global_load_lds_dwordx4 v130, s[34:35]
	s_add_i32 m0, s36, 0x2000
	s_nop 0
	global_load_lds_dwordx4 v134, s[34:35]
	s_mov_b32 m0, s49
	s_nop 0
	global_load_lds_dwordx4 v128, s[100:101]
	s_mov_b32 m0, s50
	s_nop 0
	global_load_lds_dwordx4 v132, s[100:101]
	s_waitcnt vmcnt(8)
	s_waitcnt lgkmcnt(0)
	s_barrier
	s_setprio 1
	s_waitcnt lgkmcnt(0)
	v_mfma_f32_16x16x32_bf16 v[60:63], v[144:147], v[184:187], v[60:63]
	v_mfma_f32_16x16x32_bf16 v[56:59], v[160:163], v[184:187], v[56:59]
	v_mfma_f32_16x16x32_bf16 v[44:47], v[144:147], v[192:195], v[44:47]
	v_mfma_f32_16x16x32_bf16 v[40:43], v[160:163], v[192:195], v[40:43]
	v_mfma_f32_16x16x32_bf16 v[28:31], v[144:147], v[202:205], v[28:31]
	v_mfma_f32_16x16x32_bf16 v[24:27], v[160:163], v[202:205], v[24:27]
	v_mfma_f32_16x16x32_bf16 v[12:15], v[144:147], v[210:213], v[12:15]
	v_mfma_f32_16x16x32_bf16 v[8:11], v[160:163], v[210:213], v[8:11]
	v_mfma_f32_16x16x32_bf16 v[60:63], v[148:151], v[188:191], v[60:63]
	v_mfma_f32_16x16x32_bf16 v[56:59], v[164:167], v[188:191], v[56:59]
	v_mfma_f32_16x16x32_bf16 v[44:47], v[148:151], v[198:201], v[44:47]
	v_mfma_f32_16x16x32_bf16 v[40:43], v[164:167], v[198:201], v[40:43]
	v_mfma_f32_16x16x32_bf16 v[28:31], v[148:151], v[206:209], v[28:31]
	v_mfma_f32_16x16x32_bf16 v[24:27], v[164:167], v[206:209], v[24:27]
	v_mfma_f32_16x16x32_bf16 v[12:15], v[148:151], v[214:217], v[12:15]
	v_mfma_f32_16x16x32_bf16 v[8:11], v[164:167], v[214:217], v[8:11]
	s_setprio 0
	s_setprio 1
	v_mfma_f32_16x16x32_bf16 v[52:55], v[168:171], v[184:187], v[52:55]
	v_mfma_f32_16x16x32_bf16 v[48:51], v[176:179], v[184:187], v[48:51]
	v_mfma_f32_16x16x32_bf16 v[36:39], v[168:171], v[192:195], v[36:39]
	v_mfma_f32_16x16x32_bf16 v[32:35], v[176:179], v[192:195], v[32:35]
	v_mfma_f32_16x16x32_bf16 v[20:23], v[168:171], v[202:205], v[20:23]
	v_mfma_f32_16x16x32_bf16 v[16:19], v[176:179], v[202:205], v[16:19]
	v_mfma_f32_16x16x32_bf16 v[4:7], v[168:171], v[210:213], v[4:7]
	v_mfma_f32_16x16x32_bf16 v[0:3], v[176:179], v[210:213], v[0:3]
	v_mfma_f32_16x16x32_bf16 v[52:55], v[172:175], v[188:191], v[52:55]
	v_mfma_f32_16x16x32_bf16 v[48:51], v[180:183], v[188:191], v[48:51]
	v_mfma_f32_16x16x32_bf16 v[36:39], v[172:175], v[198:201], v[36:39]
	v_mfma_f32_16x16x32_bf16 v[32:35], v[180:183], v[198:201], v[32:35]
	v_mfma_f32_16x16x32_bf16 v[20:23], v[172:175], v[206:209], v[20:23]
	v_mfma_f32_16x16x32_bf16 v[16:19], v[180:183], v[206:209], v[16:19]
	v_mfma_f32_16x16x32_bf16 v[4:7], v[172:175], v[214:217], v[4:7]
	v_mfma_f32_16x16x32_bf16 v[0:3], v[180:183], v[214:217], v[0:3]
	s_setprio 0
	s_barrier
	s_add_i32 s58, s58, 2
	s_add_u32 s56, s56, 0x100
	s_addc_u32 s57, s57, 0
	s_add_u32 s26, s26, 0x100
	s_addc_u32 s27, s27, 0
	s_cmp_gt_u32 s58, 13
	s_cbranch_scc0 .LBB0_1823
	s_nop 0
	s_nop 0
	s_nop 0
	s_nop 0
	s_and_b64 vcc, exec, s[14:15]
	s_cbranch_vccz .LBB0_1826
	s_barrier
